# p_convert in-loop tile loads: per-row kscale multiply deferred to the loop-top wait instead of four vmcnt(0) drains per tile (same multiply, bit-identical)
# speedup vs baseline: 1.0090x; 1.0017x over previous
; #define LAS __attribute__((address_space(3)))
; DI void p_convert(const Frame& F) {
;     LAS unsigned* ts = (LAS unsigned*)F.lds;
;     int t = F.vcu; CvTile cur = cv_tile(F, t), nx1 = cv_tile(F, t + F.G); f32x4 r0[4], r1[4]; int buf = 0;
;     if (cur.ok) cv_load(F, cur, r0);
;     if (nx1.ok) cv_load(F, nx1, r1);
;     while (cur.ok) {
.LBB0_271:
	s_and_b64 vcc, exec, s[4:5]
	s_cbranch_vccnz .LBB0_342
	v_ashrrev_i32_e32 v0, 4, v130
	s_movk_i32 s4, 0x104
	v_mul_lo_u32 v3, v0, s4
	s_lshl_b32 s4, s64, 1
	v_readlane_b32 s12, v254, 55
	v_readlane_b32 s13, v254, 56
	s_add_u32 s38, s12, 0x3500000
	s_addc_u32 s39, s13, 0
	s_add_u32 s52, s12, 0x2500000
	s_addc_u32 s53, s13, 0
	s_add_u32 s57, s12, 0x1d00000
	s_addc_u32 s58, s13, 0
	v_lshlrev_b32_e32 v0, 2, v130
	s_add_u32 s59, s12, 0x1a00000
	v_and_b32_e32 v2, 60, v0
	s_addc_u32 s60, s13, 0
	v_and_b32_e32 v0, 7, v130
	s_add_u32 s61, s12, 0x8d00000
	v_ashrrev_i32_e32 v10, 3, v130
	v_mul_u32_u24_e32 v13, 0x410, v0
	v_lshlrev_b32_e32 v0, 3, v0
	s_addc_u32 s62, s13, 0
	v_and_b32_e32 v11, -2, v10
	v_or_b32_e32 v12, 1, v10
	s_add_i32 s63, s69, s4
	s_mov_b32 s71, 0
	v_lshlrev_b32_e32 v4, 1, v0
	s_mov_b32 s100, 0
	v_mov_b32_e32 v184, 1.0
	v_mov_b32_e32 v186, 1.0
	v_mov_b32_e32 v188, 1.0
	v_mov_b32_e32 v190, 1.0
	s_branch .LBB0_274

; #define LAS __attribute__((address_space(3)))
; DI unsigned pk2(float a, float b) { f32x2 v = {a, b}; bfv2 r = __builtin_convertvector(v, bfv2); return __builtin_bit_cast(unsigned, r); }
; DI CvTile cv_tile(const Frame& F, int t) {
;     CvTile r; r.ok = false;
;     constexpr int NTN[6] = {26, 12, 16, 16, 88, 16}, NT_[6] = {26 * 32, 12 * 8, 16 * 8, 16 * 32, 88 * 32, 16 * 88};
;     constexpr int PER_LAYER = NT_[0] + NT_[1] + NT_[2] + NT_[3] + NT_[4] + NT_[5];
;     if (t >= 2 * PER_LAYER) return r;
;     const int l = t >= PER_LAYER ? 1 : 0; t -= l * PER_LAYER;
;     int j = 0, nt = 0, kt = 0;
; #pragma unroll
;     for (int q = 0; q < 6; ++q) { if (t >= 0 && t < NT_[q]) { j = q; nt = t % NTN[q]; kt = t / NTN[q]; } t -= NT_[q]; }
; DI void p_convert(const Frame& F) {
;     ...
;     while (cur.ok) {
;         LAS unsigned* tb = ts + buf * (2 * 32 * 65);
; #pragma unroll
;         for (int h = 0; h < 2; ++h) { LAS unsigned* q = tb + h * (32 * 65) + (F.tid >> 4) * 65 + (F.tid & 15) * 4;
; #pragma unroll
;             for (int i = 0; i < 4; ++i) q[i] = pk2(r0[h * 2][i], r0[h * 2 + 1][i]); }
;         __syncthreads();
; #pragma unroll
;         for (int i = 0; i < 4; ++i) r0[i] = r1[i];
;         const CvTile nx2 = cv_tile(F, t + 2 * F.G);
.LBB0_274:
	s_waitcnt vmcnt(0)
	s_cmp_eq_u32 s100, 0
	s_cbranch_scc1 .Lcv_nomul
	v_pk_mul_f32 v[34:35], v[34:35], v[184:185] op_sel_hi:[1,0]
	v_pk_mul_f32 v[32:33], v[32:33], v[184:185] op_sel_hi:[1,0]
	v_pk_mul_f32 v[38:39], v[38:39], v[186:187] op_sel_hi:[1,0]
	v_pk_mul_f32 v[36:37], v[36:37], v[186:187] op_sel_hi:[1,0]
	v_pk_mul_f32 v[42:43], v[42:43], v[188:189] op_sel_hi:[1,0]
	v_pk_mul_f32 v[40:41], v[40:41], v[188:189] op_sel_hi:[1,0]
	v_pk_mul_f32 v[46:47], v[46:47], v[190:191] op_sel_hi:[1,0]
	v_pk_mul_f32 v[44:45], v[44:45], v[190:191] op_sel_hi:[1,0]
	s_mov_b32 s100, 0
.Lcv_nomul:
	v_mov_b32_e32 v184, 1.0
	v_mov_b32_e32 v186, 1.0
	v_mov_b32_e32 v188, 1.0
	v_mov_b32_e32 v190, 1.0
	v_mov_b64_e32 v[62:63], v[30:31]
	s_mul_i32 s4, s71, 0x4100
	v_mov_b64_e32 v[52:53], v[20:21]
	v_mov_b64_e32 v[48:49], v[16:17]
	s_add_i32 s69, s4, 0
	v_lshlrev_b32_e32 v0, 2, v2
	v_mov_b64_e32 v[54:55], v[22:23]
	v_mov_b64_e32 v[50:51], v[18:19]
	v_add3_u32 v5, s69, v3, v0
	v_cvt_pk_bf16_f32 v6, v48, v52
	v_cvt_pk_bf16_f32 v7, v49, v53
	v_mov_b64_e32 v[60:61], v[28:29]
	v_mov_b64_e32 v[56:57], v[24:25]
	ds_write2_b32 v5, v6, v7 offset1:1
	v_cvt_pk_bf16_f32 v6, v50, v54
	v_cvt_pk_bf16_f32 v7, v51, v55
	v_mov_b64_e32 v[58:59], v[26:27]
	v_mov_b64_e32 v[16:17], v[32:33]
	ds_write2_b32 v5, v6, v7 offset0:2 offset1:3
	v_add_u32_e32 v6, 0x2080, v5
	v_cvt_pk_bf16_f32 v7, v56, v60
	v_cvt_pk_bf16_f32 v8, v57, v61
	s_cmpk_lt_i32 s63, 0x2d40
	v_mov_b64_e32 v[18:19], v[34:35]
	v_mov_b64_e32 v[20:21], v[36:37]
	v_mov_b64_e32 v[22:23], v[38:39]
	v_mov_b64_e32 v[24:25], v[40:41]
	v_mov_b64_e32 v[26:27], v[42:43]
	v_mov_b64_e32 v[28:29], v[44:45]
	v_mov_b64_e32 v[30:31], v[46:47]
	ds_write2_b32 v6, v7, v8 offset1:1
	v_cvt_pk_bf16_f32 v6, v58, v62
	v_add_u32_e32 v5, 0x2088, v5
	v_cvt_pk_bf16_f32 v7, v59, v63
	s_cselect_b64 s[4:5], -1, 0
	s_cmpk_gt_i32 s63, 0x2d3f
	ds_write2_b32 v5, v6, v7 offset1:1
	s_waitcnt lgkmcnt(0)
	s_barrier
	s_cbranch_scc1 .LBB0_319
	s_cmpk_gt_i32 s63, 0x169f
	s_cselect_b64 s[12:13], -1, 0
	s_and_b64 s[14:15], s[12:13], exec
	s_cselect_b32 s91, 0xffffe960, 0
	s_add_i32 s91, s91, s63
	s_mov_b32 s7, 0
	s_cmpk_lt_u32 s91, 0x340
	s_mov_b32 s15, 0
	s_mov_b32 s14, 0
	s_cbranch_scc0 .LBB0_277
	s_and_b32 s14, s91, 0xffff
	s_mulk_i32 s14, 0x4ec5
	s_lshr_b32 s14, s14, 19
	s_mul_i32 s15, s14, 26
	s_sub_i32 s15, s91, s15
	s_and_b32 s15, s15, 0xffff

; DI void cv_load(const Frame& F, const CvTile& t, f32x4 (&r)[4]) {
; #pragma unroll
;     for (int h = 0; h < 2; ++h) { const int sc = h ? t.sc1 : t.sc0;
; #pragma unroll
;         for (int p = 0; p < 2; ++p) { const int kk = 2 * (F.tid >> 4) + p;
;             f32x4 v = {0.f, 0.f, 0.f, 0.f};
;             if (sc >= 0) { v = __builtin_nontemporal_load((const f32x4*)(t.src + (size_t)(t.k0 + kk) * t.Nsrc + sc + (F.tid & 15) * 4)); if (t.kscale) v *= t.kscale[t.k0 + kk]; }
;             r[h * 2 + p] = v; } }
.LBB0_322:
	v_mov_b32_e32 v39, 0
	s_andn2_b64 vcc, exec, s[42:43]
	v_add_u32_e32 v6, s34, v11
	v_mov_b32_e32 v38, 0
	v_mov_b32_e32 v37, 0
	v_mov_b32_e32 v36, 0
	v_mov_b32_e32 v35, 0
	v_mov_b32_e32 v34, v39
	v_mov_b32_e32 v33, v39
	v_mov_b32_e32 v32, v39
	s_cbranch_vccnz .LBB0_327
	v_mad_i64_i32 v[8:9], s[18:19], v6, s7, 0
	v_lshl_add_u64 v[8:9], v[8:9], 2, s[14:15]
	v_lshl_add_u64 v[8:9], s[22:23], 2, v[8:9]
	v_lshl_add_u64 v[8:9], v[8:9], 0, v[0:1]
	global_load_dwordx4 v[32:35], v[8:9], off nt
	s_cmp_lg_u64 s[36:37], 0
	s_cselect_b64 s[42:43], -1, 0
	s_cmp_eq_u64 s[36:37], 0
	s_cbranch_scc1 .LBB0_325
	v_ashrrev_i32_e32 v7, 31, v6
	v_lshl_add_u64 v[8:9], v[6:7], 2, s[36:37]
	global_load_dword v184, v[8:9], off
	s_mov_b32 s100, 1
.LBB0_325:
	v_add_u32_e32 v8, s34, v12
	v_mad_i64_i32 v[14:15], s[18:19], v8, s7, 0
	v_lshl_add_u64 v[14:15], v[14:15], 2, s[14:15]
	v_lshl_add_u64 v[14:15], s[22:23], 2, v[14:15]
	v_lshl_add_u64 v[14:15], v[14:15], 0, v[0:1]
	global_load_dwordx4 v[36:39], v[14:15], off nt
	s_andn2_b64 vcc, exec, s[42:43]
	s_cbranch_vccnz .LBB0_327
	v_ashrrev_i32_e32 v9, 31, v8
	v_lshl_add_u64 v[8:9], v[8:9], 2, s[36:37]
	global_load_dword v186, v[8:9], off
	s_mov_b32 s100, 1

; DI void cv_load(const Frame& F, const CvTile& t, f32x4 (&r)[4]) {
; #pragma unroll
;     for (int h = 0; h < 2; ++h) { const int sc = h ? t.sc1 : t.sc0;
; #pragma unroll
;         for (int p = 0; p < 2; ++p) { const int kk = 2 * (F.tid >> 4) + p;
;             f32x4 v = {0.f, 0.f, 0.f, 0.f};
;             if (sc >= 0) { v = __builtin_nontemporal_load((const f32x4*)(t.src + (size_t)(t.k0 + kk) * t.Nsrc + sc + (F.tid & 15) * 4)); if (t.kscale) v *= t.kscale[t.k0 + kk]; }
;             r[h * 2 + p] = v; } }
.LBB0_329:
	v_mov_b32_e32 v47, 0
	s_andn2_b64 vcc, exec, s[42:43]
	v_mov_b32_e32 v46, 0
	v_mov_b32_e32 v45, 0
	v_mov_b32_e32 v44, 0
	v_mov_b32_e32 v43, 0
	v_mov_b32_e32 v42, 0
	v_mov_b32_e32 v41, 0
	v_mov_b32_e32 v40, 0
	s_cbranch_vccnz .LBB0_273
	v_mad_i64_i32 v[8:9], s[18:19], v6, s7, 0
	s_mov_b32 s41, s23
	v_lshl_add_u64 v[8:9], v[8:9], 2, s[14:15]
	v_lshl_add_u64 v[8:9], s[40:41], 2, v[8:9]
	v_lshl_add_u64 v[8:9], v[8:9], 0, v[0:1]
	global_load_dwordx4 v[40:43], v[8:9], off nt
	s_cmp_lg_u64 s[36:37], 0
	s_cselect_b64 s[42:43], -1, 0
	s_cmp_eq_u64 s[36:37], 0
	s_cbranch_scc1 .LBB0_332
	v_ashrrev_i32_e32 v7, 31, v6
	v_lshl_add_u64 v[6:7], v[6:7], 2, s[36:37]
	global_load_dword v188, v[6:7], off
	s_mov_b32 s100, 1
.LBB0_332:
	v_add_u32_e32 v6, s34, v12
	v_mad_i64_i32 v[8:9], s[18:19], v6, s7, 0
	v_lshl_add_u64 v[8:9], v[8:9], 2, s[14:15]
	v_lshl_add_u64 v[8:9], s[40:41], 2, v[8:9]
	v_lshl_add_u64 v[8:9], v[8:9], 0, v[0:1]
	global_load_dwordx4 v[44:47], v[8:9], off nt
	s_andn2_b64 vcc, exec, s[42:43]
	s_cbranch_vccnz .LBB0_273
	v_ashrrev_i32_e32 v7, 31, v6
	v_lshl_add_u64 v[6:7], v[6:7], 2, s[36:37]
	global_load_dword v190, v[6:7], off
	s_mov_b32 s100, 1
	s_branch .LBB0_273
